# batched double-buffered compressed-KV page conversion loop in P0 (16 rows in flight instead of 1)
# speedup vs baseline: 1.0109x; 1.0109x over previous
.LBB0_99:
	v_lshl_add_u64 v[10:11], v[4:5], 0, s[4:5]
	global_load_dwordx4 v[120:123], v[10:11], off
	global_load_dwordx4 v[124:127], v[10:11], off offset:2048
	v_add_co_u32_e32 v12, vcc, 0x1000, v10
	s_nop 1
	v_addc_co_u32_e32 v13, vcc, 0, v11, vcc
	global_load_dwordx4 v[128:131], v[12:13], off
	global_load_dwordx4 v[132:135], v[12:13], off offset:2048
	v_add_co_u32_e32 v12, vcc, 0x2000, v10
	s_nop 1
	v_addc_co_u32_e32 v13, vcc, 0, v11, vcc
	global_load_dwordx4 v[136:139], v[12:13], off
	global_load_dwordx4 v[140:143], v[12:13], off offset:2048
	v_add_co_u32_e32 v12, vcc, 0x3000, v10
	s_nop 1
	v_addc_co_u32_e32 v13, vcc, 0, v11, vcc
	global_load_dwordx4 v[144:147], v[12:13], off
	global_load_dwordx4 v[148:151], v[12:13], off offset:2048
	v_add_co_u32_e32 v12, vcc, 0x4000, v10
	s_nop 1
	v_addc_co_u32_e32 v13, vcc, 0, v11, vcc
	global_load_dwordx4 v[152:155], v[12:13], off
	global_load_dwordx4 v[156:159], v[12:13], off offset:2048
	v_add_co_u32_e32 v12, vcc, 0x5000, v10
	s_nop 1
	v_addc_co_u32_e32 v13, vcc, 0, v11, vcc
	global_load_dwordx4 v[160:163], v[12:13], off
	global_load_dwordx4 v[164:167], v[12:13], off offset:2048
	v_add_co_u32_e32 v12, vcc, 0x6000, v10
	s_nop 1
	v_addc_co_u32_e32 v13, vcc, 0, v11, vcc
	global_load_dwordx4 v[168:171], v[12:13], off
	global_load_dwordx4 v[172:175], v[12:13], off offset:2048
	v_add_co_u32_e32 v12, vcc, 0x7000, v10
	s_nop 1
	v_addc_co_u32_e32 v13, vcc, 0, v11, vcc
	global_load_dwordx4 v[176:179], v[12:13], off
	global_load_dwordx4 v[180:183], v[12:13], off offset:2048
	v_add_co_u32_e32 v10, vcc, 0x8000, v10
	s_nop 1
	v_addc_co_u32_e32 v11, vcc, 0, v11, vcc
	global_load_dwordx4 v[184:187], v[10:11], off
	global_load_dwordx4 v[188:191], v[10:11], off offset:2048
	v_add_co_u32_e32 v12, vcc, 0x1000, v10
	s_nop 1
	v_addc_co_u32_e32 v13, vcc, 0, v11, vcc
	global_load_dwordx4 v[192:195], v[12:13], off
	global_load_dwordx4 v[196:199], v[12:13], off offset:2048
	v_add_co_u32_e32 v12, vcc, 0x2000, v10
	s_nop 1
	v_addc_co_u32_e32 v13, vcc, 0, v11, vcc
	global_load_dwordx4 v[200:203], v[12:13], off
	global_load_dwordx4 v[208:211], v[12:13], off offset:2048
	v_add_co_u32_e32 v12, vcc, 0x3000, v10
	s_nop 1
	v_addc_co_u32_e32 v13, vcc, 0, v11, vcc
	global_load_dwordx4 v[212:215], v[12:13], off
	global_load_dwordx4 v[216:219], v[12:13], off offset:2048
	v_add_co_u32_e32 v12, vcc, 0x4000, v10
	s_nop 1
	v_addc_co_u32_e32 v13, vcc, 0, v11, vcc
	global_load_dwordx4 v[220:223], v[12:13], off
	global_load_dwordx4 v[224:227], v[12:13], off offset:2048
	v_add_co_u32_e32 v12, vcc, 0x5000, v10
	s_nop 1
	v_addc_co_u32_e32 v13, vcc, 0, v11, vcc
	global_load_dwordx4 v[228:231], v[12:13], off
	global_load_dwordx4 v[232:235], v[12:13], off offset:2048
	v_add_co_u32_e32 v12, vcc, 0x6000, v10
	s_nop 1
	v_addc_co_u32_e32 v13, vcc, 0, v11, vcc
	global_load_dwordx4 v[236:239], v[12:13], off
	global_load_dwordx4 v[240:243], v[12:13], off offset:2048
	v_add_co_u32_e32 v12, vcc, 0x7000, v10
	s_nop 1
	v_addc_co_u32_e32 v13, vcc, 0, v11, vcc
	global_load_dwordx4 v[244:247], v[12:13], off
	global_load_dwordx4 v[248:251], v[12:13], off offset:2048
	s_waitcnt vmcnt(16)
	v_cvt_pk_bf16_f32 v120, v120, v121
	v_cvt_pk_bf16_f32 v121, v122, v123
	v_cvt_pk_bf16_f32 v124, v124, v125
	v_cvt_pk_bf16_f32 v125, v126, v127
	v_cvt_pk_bf16_f32 v128, v128, v129
	v_cvt_pk_bf16_f32 v129, v130, v131
	v_cvt_pk_bf16_f32 v132, v132, v133
	v_cvt_pk_bf16_f32 v133, v134, v135
	v_cvt_pk_bf16_f32 v136, v136, v137
	v_cvt_pk_bf16_f32 v137, v138, v139
	v_cvt_pk_bf16_f32 v140, v140, v141
	v_cvt_pk_bf16_f32 v141, v142, v143
	v_cvt_pk_bf16_f32 v144, v144, v145
	v_cvt_pk_bf16_f32 v145, v146, v147
	v_cvt_pk_bf16_f32 v148, v148, v149
	v_cvt_pk_bf16_f32 v149, v150, v151
	v_cvt_pk_bf16_f32 v152, v152, v153
	v_cvt_pk_bf16_f32 v153, v154, v155
	v_cvt_pk_bf16_f32 v156, v156, v157
	v_cvt_pk_bf16_f32 v157, v158, v159
	v_cvt_pk_bf16_f32 v160, v160, v161
	v_cvt_pk_bf16_f32 v161, v162, v163
	v_cvt_pk_bf16_f32 v164, v164, v165
	v_cvt_pk_bf16_f32 v165, v166, v167
	v_cvt_pk_bf16_f32 v168, v168, v169
	v_cvt_pk_bf16_f32 v169, v170, v171
	v_cvt_pk_bf16_f32 v172, v172, v173
	v_cvt_pk_bf16_f32 v173, v174, v175
	v_cvt_pk_bf16_f32 v176, v176, v177
	v_cvt_pk_bf16_f32 v177, v178, v179
	v_cvt_pk_bf16_f32 v180, v180, v181
	v_cvt_pk_bf16_f32 v181, v182, v183
	global_store_dwordx2 v[2:3], v[120:121], off offset:-1024
	global_store_dwordx2 v[2:3], v[124:125], off offset:-896
	global_store_dwordx2 v[2:3], v[128:129], off offset:-768
	global_store_dwordx2 v[2:3], v[132:133], off offset:-640
	global_store_dwordx2 v[2:3], v[136:137], off offset:-512
	global_store_dwordx2 v[2:3], v[140:141], off offset:-384
	global_store_dwordx2 v[2:3], v[144:145], off offset:-256
	global_store_dwordx2 v[2:3], v[148:149], off offset:-128
	global_store_dwordx2 v[2:3], v[152:153], off
	global_store_dwordx2 v[2:3], v[156:157], off offset:128
	global_store_dwordx2 v[2:3], v[160:161], off offset:256
	global_store_dwordx2 v[2:3], v[164:165], off offset:384
	global_store_dwordx2 v[2:3], v[168:169], off offset:512
	global_store_dwordx2 v[2:3], v[172:173], off offset:640
	global_store_dwordx2 v[2:3], v[176:177], off offset:768
	global_store_dwordx2 v[2:3], v[180:181], off offset:896
	s_mov_b64 s[16:17], 0x800
	v_lshl_add_u64 v[2:3], v[2:3], 0, s[16:17]
	v_add_co_u32_e32 v10, vcc, 0x8000, v10
	s_nop 1
	v_addc_co_u32_e32 v11, vcc, 0, v11, vcc
	global_load_dwordx4 v[120:123], v[10:11], off
	global_load_dwordx4 v[124:127], v[10:11], off offset:2048
	v_add_co_u32_e32 v12, vcc, 0x1000, v10
	s_nop 1
	v_addc_co_u32_e32 v13, vcc, 0, v11, vcc
	global_load_dwordx4 v[128:131], v[12:13], off
	global_load_dwordx4 v[132:135], v[12:13], off offset:2048
	v_add_co_u32_e32 v12, vcc, 0x2000, v10
	s_nop 1
	v_addc_co_u32_e32 v13, vcc, 0, v11, vcc
	global_load_dwordx4 v[136:139], v[12:13], off
	global_load_dwordx4 v[140:143], v[12:13], off offset:2048
	v_add_co_u32_e32 v12, vcc, 0x3000, v10
	s_nop 1
	v_addc_co_u32_e32 v13, vcc, 0, v11, vcc
	global_load_dwordx4 v[144:147], v[12:13], off
	global_load_dwordx4 v[148:151], v[12:13], off offset:2048
	v_add_co_u32_e32 v12, vcc, 0x4000, v10
	s_nop 1
	v_addc_co_u32_e32 v13, vcc, 0, v11, vcc
	global_load_dwordx4 v[152:155], v[12:13], off
	global_load_dwordx4 v[156:159], v[12:13], off offset:2048
	v_add_co_u32_e32 v12, vcc, 0x5000, v10
	s_nop 1
	v_addc_co_u32_e32 v13, vcc, 0, v11, vcc
	global_load_dwordx4 v[160:163], v[12:13], off
	global_load_dwordx4 v[164:167], v[12:13], off offset:2048
	v_add_co_u32_e32 v12, vcc, 0x6000, v10
	s_nop 1
	v_addc_co_u32_e32 v13, vcc, 0, v11, vcc
	global_load_dwordx4 v[168:171], v[12:13], off
	global_load_dwordx4 v[172:175], v[12:13], off offset:2048
	v_add_co_u32_e32 v12, vcc, 0x7000, v10
	s_nop 1
	v_addc_co_u32_e32 v13, vcc, 0, v11, vcc
	global_load_dwordx4 v[176:179], v[12:13], off
	global_load_dwordx4 v[180:183], v[12:13], off offset:2048
	s_waitcnt vmcnt(32)
	v_cvt_pk_bf16_f32 v184, v184, v185
	v_cvt_pk_bf16_f32 v185, v186, v187
	v_cvt_pk_bf16_f32 v188, v188, v189
	v_cvt_pk_bf16_f32 v189, v190, v191
	v_cvt_pk_bf16_f32 v192, v192, v193
	v_cvt_pk_bf16_f32 v193, v194, v195
	v_cvt_pk_bf16_f32 v196, v196, v197
	v_cvt_pk_bf16_f32 v197, v198, v199
	v_cvt_pk_bf16_f32 v200, v200, v201
	v_cvt_pk_bf16_f32 v201, v202, v203
	v_cvt_pk_bf16_f32 v208, v208, v209
	v_cvt_pk_bf16_f32 v209, v210, v211
	v_cvt_pk_bf16_f32 v212, v212, v213
	v_cvt_pk_bf16_f32 v213, v214, v215
	v_cvt_pk_bf16_f32 v216, v216, v217
	v_cvt_pk_bf16_f32 v217, v218, v219
	v_cvt_pk_bf16_f32 v220, v220, v221
	v_cvt_pk_bf16_f32 v221, v222, v223
	v_cvt_pk_bf16_f32 v224, v224, v225
	v_cvt_pk_bf16_f32 v225, v226, v227
	v_cvt_pk_bf16_f32 v228, v228, v229
	v_cvt_pk_bf16_f32 v229, v230, v231
	v_cvt_pk_bf16_f32 v232, v232, v233
	v_cvt_pk_bf16_f32 v233, v234, v235
	v_cvt_pk_bf16_f32 v236, v236, v237
	v_cvt_pk_bf16_f32 v237, v238, v239
	v_cvt_pk_bf16_f32 v240, v240, v241
	v_cvt_pk_bf16_f32 v241, v242, v243
	v_cvt_pk_bf16_f32 v244, v244, v245
	v_cvt_pk_bf16_f32 v245, v246, v247
	v_cvt_pk_bf16_f32 v248, v248, v249
	v_cvt_pk_bf16_f32 v249, v250, v251
	global_store_dwordx2 v[2:3], v[184:185], off offset:-1024
	global_store_dwordx2 v[2:3], v[188:189], off offset:-896
	global_store_dwordx2 v[2:3], v[192:193], off offset:-768
	global_store_dwordx2 v[2:3], v[196:197], off offset:-640
	global_store_dwordx2 v[2:3], v[200:201], off offset:-512
	global_store_dwordx2 v[2:3], v[208:209], off offset:-384
	global_store_dwordx2 v[2:3], v[212:213], off offset:-256
	global_store_dwordx2 v[2:3], v[216:217], off offset:-128
	global_store_dwordx2 v[2:3], v[220:221], off
	global_store_dwordx2 v[2:3], v[224:225], off offset:128
	global_store_dwordx2 v[2:3], v[228:229], off offset:256
	global_store_dwordx2 v[2:3], v[232:233], off offset:384
	global_store_dwordx2 v[2:3], v[236:237], off offset:512
	global_store_dwordx2 v[2:3], v[240:241], off offset:640
	global_store_dwordx2 v[2:3], v[244:245], off offset:768
	global_store_dwordx2 v[2:3], v[248:249], off offset:896
	s_mov_b64 s[16:17], 0x800
	v_lshl_add_u64 v[2:3], v[2:3], 0, s[16:17]
	v_add_co_u32_e32 v10, vcc, 0x8000, v10
	s_nop 1
	v_addc_co_u32_e32 v11, vcc, 0, v11, vcc
	global_load_dwordx4 v[184:187], v[10:11], off
	global_load_dwordx4 v[188:191], v[10:11], off offset:2048
	v_add_co_u32_e32 v12, vcc, 0x1000, v10
	s_nop 1
	v_addc_co_u32_e32 v13, vcc, 0, v11, vcc
	global_load_dwordx4 v[192:195], v[12:13], off
	global_load_dwordx4 v[196:199], v[12:13], off offset:2048
	v_add_co_u32_e32 v12, vcc, 0x2000, v10
	s_nop 1
	v_addc_co_u32_e32 v13, vcc, 0, v11, vcc
	global_load_dwordx4 v[200:203], v[12:13], off
	global_load_dwordx4 v[208:211], v[12:13], off offset:2048
	v_add_co_u32_e32 v12, vcc, 0x3000, v10
	s_nop 1
	v_addc_co_u32_e32 v13, vcc, 0, v11, vcc
	global_load_dwordx4 v[212:215], v[12:13], off
	global_load_dwordx4 v[216:219], v[12:13], off offset:2048
	v_add_co_u32_e32 v12, vcc, 0x4000, v10
	s_nop 1
	v_addc_co_u32_e32 v13, vcc, 0, v11, vcc
	global_load_dwordx4 v[220:223], v[12:13], off
	global_load_dwordx4 v[224:227], v[12:13], off offset:2048
	v_add_co_u32_e32 v12, vcc, 0x5000, v10
	s_nop 1
	v_addc_co_u32_e32 v13, vcc, 0, v11, vcc
	global_load_dwordx4 v[228:231], v[12:13], off
	global_load_dwordx4 v[232:235], v[12:13], off offset:2048
	v_add_co_u32_e32 v12, vcc, 0x6000, v10
	s_nop 1
	v_addc_co_u32_e32 v13, vcc, 0, v11, vcc
	global_load_dwordx4 v[236:239], v[12:13], off
	global_load_dwordx4 v[240:243], v[12:13], off offset:2048
	v_add_co_u32_e32 v12, vcc, 0x7000, v10
	s_nop 1
	v_addc_co_u32_e32 v13, vcc, 0, v11, vcc
	global_load_dwordx4 v[244:247], v[12:13], off
	global_load_dwordx4 v[248:251], v[12:13], off offset:2048
	s_waitcnt vmcnt(32)
	v_cvt_pk_bf16_f32 v120, v120, v121
	v_cvt_pk_bf16_f32 v121, v122, v123
	v_cvt_pk_bf16_f32 v124, v124, v125
	v_cvt_pk_bf16_f32 v125, v126, v127
	v_cvt_pk_bf16_f32 v128, v128, v129
	v_cvt_pk_bf16_f32 v129, v130, v131
	v_cvt_pk_bf16_f32 v132, v132, v133
	v_cvt_pk_bf16_f32 v133, v134, v135
	v_cvt_pk_bf16_f32 v136, v136, v137
	v_cvt_pk_bf16_f32 v137, v138, v139
	v_cvt_pk_bf16_f32 v140, v140, v141
	v_cvt_pk_bf16_f32 v141, v142, v143
	v_cvt_pk_bf16_f32 v144, v144, v145
	v_cvt_pk_bf16_f32 v145, v146, v147
	v_cvt_pk_bf16_f32 v148, v148, v149
	v_cvt_pk_bf16_f32 v149, v150, v151
	v_cvt_pk_bf16_f32 v152, v152, v153
	v_cvt_pk_bf16_f32 v153, v154, v155
	v_cvt_pk_bf16_f32 v156, v156, v157
	v_cvt_pk_bf16_f32 v157, v158, v159
	v_cvt_pk_bf16_f32 v160, v160, v161
	v_cvt_pk_bf16_f32 v161, v162, v163
	v_cvt_pk_bf16_f32 v164, v164, v165
	v_cvt_pk_bf16_f32 v165, v166, v167
	v_cvt_pk_bf16_f32 v168, v168, v169
	v_cvt_pk_bf16_f32 v169, v170, v171
	v_cvt_pk_bf16_f32 v172, v172, v173
	v_cvt_pk_bf16_f32 v173, v174, v175
	v_cvt_pk_bf16_f32 v176, v176, v177
	v_cvt_pk_bf16_f32 v177, v178, v179
	v_cvt_pk_bf16_f32 v180, v180, v181
	v_cvt_pk_bf16_f32 v181, v182, v183
	global_store_dwordx2 v[2:3], v[120:121], off offset:-1024
	global_store_dwordx2 v[2:3], v[124:125], off offset:-896
	global_store_dwordx2 v[2:3], v[128:129], off offset:-768
	global_store_dwordx2 v[2:3], v[132:133], off offset:-640
	global_store_dwordx2 v[2:3], v[136:137], off offset:-512
	global_store_dwordx2 v[2:3], v[140:141], off offset:-384
	global_store_dwordx2 v[2:3], v[144:145], off offset:-256
	global_store_dwordx2 v[2:3], v[148:149], off offset:-128
	global_store_dwordx2 v[2:3], v[152:153], off
	global_store_dwordx2 v[2:3], v[156:157], off offset:128
	global_store_dwordx2 v[2:3], v[160:161], off offset:256
	global_store_dwordx2 v[2:3], v[164:165], off offset:384
	global_store_dwordx2 v[2:3], v[168:169], off offset:512
	global_store_dwordx2 v[2:3], v[172:173], off offset:640
	global_store_dwordx2 v[2:3], v[176:177], off offset:768
	global_store_dwordx2 v[2:3], v[180:181], off offset:896
	s_mov_b64 s[16:17], 0x800
	v_lshl_add_u64 v[2:3], v[2:3], 0, s[16:17]
	v_add_co_u32_e32 v10, vcc, 0x8000, v10
	s_nop 1
	v_addc_co_u32_e32 v11, vcc, 0, v11, vcc
	global_load_dwordx4 v[120:123], v[10:11], off
	global_load_dwordx4 v[124:127], v[10:11], off offset:2048
	v_add_co_u32_e32 v12, vcc, 0x1000, v10
	s_nop 1
	v_addc_co_u32_e32 v13, vcc, 0, v11, vcc
	global_load_dwordx4 v[128:131], v[12:13], off
	global_load_dwordx4 v[132:135], v[12:13], off offset:2048
	v_add_co_u32_e32 v12, vcc, 0x2000, v10
	s_nop 1
	v_addc_co_u32_e32 v13, vcc, 0, v11, vcc
	global_load_dwordx4 v[136:139], v[12:13], off
	global_load_dwordx4 v[140:143], v[12:13], off offset:2048
	v_add_co_u32_e32 v12, vcc, 0x3000, v10
	s_nop 1
	v_addc_co_u32_e32 v13, vcc, 0, v11, vcc
	global_load_dwordx4 v[144:147], v[12:13], off
	global_load_dwordx4 v[148:151], v[12:13], off offset:2048
	v_add_co_u32_e32 v12, vcc, 0x4000, v10
	s_nop 1
	v_addc_co_u32_e32 v13, vcc, 0, v11, vcc
	global_load_dwordx4 v[152:155], v[12:13], off
	global_load_dwordx4 v[156:159], v[12:13], off offset:2048
	v_add_co_u32_e32 v12, vcc, 0x5000, v10
	s_nop 1
	v_addc_co_u32_e32 v13, vcc, 0, v11, vcc
	global_load_dwordx4 v[160:163], v[12:13], off
	global_load_dwordx4 v[164:167], v[12:13], off offset:2048
	v_add_co_u32_e32 v12, vcc, 0x6000, v10
	s_nop 1
	v_addc_co_u32_e32 v13, vcc, 0, v11, vcc
	global_load_dwordx4 v[168:171], v[12:13], off
	global_load_dwordx4 v[172:175], v[12:13], off offset:2048
	v_add_co_u32_e32 v12, vcc, 0x7000, v10
	s_nop 1
	v_addc_co_u32_e32 v13, vcc, 0, v11, vcc
	global_load_dwordx4 v[176:179], v[12:13], off
	global_load_dwordx4 v[180:183], v[12:13], off offset:2048
	s_waitcnt vmcnt(32)
	v_cvt_pk_bf16_f32 v184, v184, v185
	v_cvt_pk_bf16_f32 v185, v186, v187
	v_cvt_pk_bf16_f32 v188, v188, v189
	v_cvt_pk_bf16_f32 v189, v190, v191
	v_cvt_pk_bf16_f32 v192, v192, v193
	v_cvt_pk_bf16_f32 v193, v194, v195
	v_cvt_pk_bf16_f32 v196, v196, v197
	v_cvt_pk_bf16_f32 v197, v198, v199
	v_cvt_pk_bf16_f32 v200, v200, v201
	v_cvt_pk_bf16_f32 v201, v202, v203
	v_cvt_pk_bf16_f32 v208, v208, v209
	v_cvt_pk_bf16_f32 v209, v210, v211
	v_cvt_pk_bf16_f32 v212, v212, v213
	v_cvt_pk_bf16_f32 v213, v214, v215
	v_cvt_pk_bf16_f32 v216, v216, v217
	v_cvt_pk_bf16_f32 v217, v218, v219
	v_cvt_pk_bf16_f32 v220, v220, v221
	v_cvt_pk_bf16_f32 v221, v222, v223
	v_cvt_pk_bf16_f32 v224, v224, v225
	v_cvt_pk_bf16_f32 v225, v226, v227
	v_cvt_pk_bf16_f32 v228, v228, v229
	v_cvt_pk_bf16_f32 v229, v230, v231
	v_cvt_pk_bf16_f32 v232, v232, v233
	v_cvt_pk_bf16_f32 v233, v234, v235
	v_cvt_pk_bf16_f32 v236, v236, v237
	v_cvt_pk_bf16_f32 v237, v238, v239
	v_cvt_pk_bf16_f32 v240, v240, v241
	v_cvt_pk_bf16_f32 v241, v242, v243
	v_cvt_pk_bf16_f32 v244, v244, v245
	v_cvt_pk_bf16_f32 v245, v246, v247
	v_cvt_pk_bf16_f32 v248, v248, v249
	v_cvt_pk_bf16_f32 v249, v250, v251
	global_store_dwordx2 v[2:3], v[184:185], off offset:-1024
	global_store_dwordx2 v[2:3], v[188:189], off offset:-896
	global_store_dwordx2 v[2:3], v[192:193], off offset:-768
	global_store_dwordx2 v[2:3], v[196:197], off offset:-640
	global_store_dwordx2 v[2:3], v[200:201], off offset:-512
	global_store_dwordx2 v[2:3], v[208:209], off offset:-384
	global_store_dwordx2 v[2:3], v[212:213], off offset:-256
	global_store_dwordx2 v[2:3], v[216:217], off offset:-128
	global_store_dwordx2 v[2:3], v[220:221], off
	global_store_dwordx2 v[2:3], v[224:225], off offset:128
	global_store_dwordx2 v[2:3], v[228:229], off offset:256
	global_store_dwordx2 v[2:3], v[232:233], off offset:384
	global_store_dwordx2 v[2:3], v[236:237], off offset:512
	global_store_dwordx2 v[2:3], v[240:241], off offset:640
	global_store_dwordx2 v[2:3], v[244:245], off offset:768
	global_store_dwordx2 v[2:3], v[248:249], off offset:896
	s_mov_b64 s[16:17], 0x800
	v_lshl_add_u64 v[2:3], v[2:3], 0, s[16:17]
	v_add_co_u32_e32 v10, vcc, 0x8000, v10
	s_nop 1
	v_addc_co_u32_e32 v11, vcc, 0, v11, vcc
	global_load_dwordx4 v[184:187], v[10:11], off
	global_load_dwordx4 v[188:191], v[10:11], off offset:2048
	v_add_co_u32_e32 v12, vcc, 0x1000, v10
	s_nop 1
	v_addc_co_u32_e32 v13, vcc, 0, v11, vcc
	global_load_dwordx4 v[192:195], v[12:13], off
	global_load_dwordx4 v[196:199], v[12:13], off offset:2048
	v_add_co_u32_e32 v12, vcc, 0x2000, v10
	s_nop 1
	v_addc_co_u32_e32 v13, vcc, 0, v11, vcc
	global_load_dwordx4 v[200:203], v[12:13], off
	global_load_dwordx4 v[208:211], v[12:13], off offset:2048
	v_add_co_u32_e32 v12, vcc, 0x3000, v10
	s_nop 1
	v_addc_co_u32_e32 v13, vcc, 0, v11, vcc
	global_load_dwordx4 v[212:215], v[12:13], off
	global_load_dwordx4 v[216:219], v[12:13], off offset:2048
	v_add_co_u32_e32 v12, vcc, 0x4000, v10
	s_nop 1
	v_addc_co_u32_e32 v13, vcc, 0, v11, vcc
	global_load_dwordx4 v[220:223], v[12:13], off
	global_load_dwordx4 v[224:227], v[12:13], off offset:2048
	v_add_co_u32_e32 v12, vcc, 0x5000, v10
	s_nop 1
	v_addc_co_u32_e32 v13, vcc, 0, v11, vcc
	global_load_dwordx4 v[228:231], v[12:13], off
	global_load_dwordx4 v[232:235], v[12:13], off offset:2048
	v_add_co_u32_e32 v12, vcc, 0x6000, v10
	s_nop 1
	v_addc_co_u32_e32 v13, vcc, 0, v11, vcc
	global_load_dwordx4 v[236:239], v[12:13], off
	global_load_dwordx4 v[240:243], v[12:13], off offset:2048
	v_add_co_u32_e32 v12, vcc, 0x7000, v10
	s_nop 1
	v_addc_co_u32_e32 v13, vcc, 0, v11, vcc
	global_load_dwordx4 v[244:247], v[12:13], off
	global_load_dwordx4 v[248:251], v[12:13], off offset:2048
	s_waitcnt vmcnt(32)
	v_cvt_pk_bf16_f32 v120, v120, v121
	v_cvt_pk_bf16_f32 v121, v122, v123
	v_cvt_pk_bf16_f32 v124, v124, v125
	v_cvt_pk_bf16_f32 v125, v126, v127
	v_cvt_pk_bf16_f32 v128, v128, v129
	v_cvt_pk_bf16_f32 v129, v130, v131
	v_cvt_pk_bf16_f32 v132, v132, v133
	v_cvt_pk_bf16_f32 v133, v134, v135
	v_cvt_pk_bf16_f32 v136, v136, v137
	v_cvt_pk_bf16_f32 v137, v138, v139
	v_cvt_pk_bf16_f32 v140, v140, v141
	v_cvt_pk_bf16_f32 v141, v142, v143
	v_cvt_pk_bf16_f32 v144, v144, v145
	v_cvt_pk_bf16_f32 v145, v146, v147
	v_cvt_pk_bf16_f32 v148, v148, v149
	v_cvt_pk_bf16_f32 v149, v150, v151
	v_cvt_pk_bf16_f32 v152, v152, v153
	v_cvt_pk_bf16_f32 v153, v154, v155
	v_cvt_pk_bf16_f32 v156, v156, v157
	v_cvt_pk_bf16_f32 v157, v158, v159
	v_cvt_pk_bf16_f32 v160, v160, v161
	v_cvt_pk_bf16_f32 v161, v162, v163
	v_cvt_pk_bf16_f32 v164, v164, v165
	v_cvt_pk_bf16_f32 v165, v166, v167
	v_cvt_pk_bf16_f32 v168, v168, v169
	v_cvt_pk_bf16_f32 v169, v170, v171
	v_cvt_pk_bf16_f32 v172, v172, v173
	v_cvt_pk_bf16_f32 v173, v174, v175
	v_cvt_pk_bf16_f32 v176, v176, v177
	v_cvt_pk_bf16_f32 v177, v178, v179
	v_cvt_pk_bf16_f32 v180, v180, v181
	v_cvt_pk_bf16_f32 v181, v182, v183
	global_store_dwordx2 v[2:3], v[120:121], off offset:-1024
	global_store_dwordx2 v[2:3], v[124:125], off offset:-896
	global_store_dwordx2 v[2:3], v[128:129], off offset:-768
	global_store_dwordx2 v[2:3], v[132:133], off offset:-640
	global_store_dwordx2 v[2:3], v[136:137], off offset:-512
	global_store_dwordx2 v[2:3], v[140:141], off offset:-384
	global_store_dwordx2 v[2:3], v[144:145], off offset:-256
	global_store_dwordx2 v[2:3], v[148:149], off offset:-128
	global_store_dwordx2 v[2:3], v[152:153], off
	global_store_dwordx2 v[2:3], v[156:157], off offset:128
	global_store_dwordx2 v[2:3], v[160:161], off offset:256
	global_store_dwordx2 v[2:3], v[164:165], off offset:384
	global_store_dwordx2 v[2:3], v[168:169], off offset:512
	global_store_dwordx2 v[2:3], v[172:173], off offset:640
	global_store_dwordx2 v[2:3], v[176:177], off offset:768
	global_store_dwordx2 v[2:3], v[180:181], off offset:896
	s_mov_b64 s[16:17], 0x800
	v_lshl_add_u64 v[2:3], v[2:3], 0, s[16:17]
	v_add_co_u32_e32 v10, vcc, 0x8000, v10
	s_nop 1
	v_addc_co_u32_e32 v11, vcc, 0, v11, vcc
	global_load_dwordx4 v[120:123], v[10:11], off
	global_load_dwordx4 v[124:127], v[10:11], off offset:2048
	v_add_co_u32_e32 v12, vcc, 0x1000, v10
	s_nop 1
	v_addc_co_u32_e32 v13, vcc, 0, v11, vcc
	global_load_dwordx4 v[128:131], v[12:13], off
	global_load_dwordx4 v[132:135], v[12:13], off offset:2048
	v_add_co_u32_e32 v12, vcc, 0x2000, v10
	s_nop 1
	v_addc_co_u32_e32 v13, vcc, 0, v11, vcc
	global_load_dwordx4 v[136:139], v[12:13], off
	global_load_dwordx4 v[140:143], v[12:13], off offset:2048
	v_add_co_u32_e32 v12, vcc, 0x3000, v10
	s_nop 1
	v_addc_co_u32_e32 v13, vcc, 0, v11, vcc
	global_load_dwordx4 v[144:147], v[12:13], off
	global_load_dwordx4 v[148:151], v[12:13], off offset:2048
	v_add_co_u32_e32 v12, vcc, 0x4000, v10
	s_nop 1
	v_addc_co_u32_e32 v13, vcc, 0, v11, vcc
	global_load_dwordx4 v[152:155], v[12:13], off
	global_load_dwordx4 v[156:159], v[12:13], off offset:2048
	v_add_co_u32_e32 v12, vcc, 0x5000, v10
	s_nop 1
	v_addc_co_u32_e32 v13, vcc, 0, v11, vcc
	global_load_dwordx4 v[160:163], v[12:13], off
	global_load_dwordx4 v[164:167], v[12:13], off offset:2048
	v_add_co_u32_e32 v12, vcc, 0x6000, v10
	s_nop 1
	v_addc_co_u32_e32 v13, vcc, 0, v11, vcc
	global_load_dwordx4 v[168:171], v[12:13], off
	global_load_dwordx4 v[172:175], v[12:13], off offset:2048
	v_add_co_u32_e32 v12, vcc, 0x7000, v10
	s_nop 1
	v_addc_co_u32_e32 v13, vcc, 0, v11, vcc
	global_load_dwordx4 v[176:179], v[12:13], off
	global_load_dwordx4 v[180:183], v[12:13], off offset:2048
	s_waitcnt vmcnt(32)
	v_cvt_pk_bf16_f32 v184, v184, v185
	v_cvt_pk_bf16_f32 v185, v186, v187
	v_cvt_pk_bf16_f32 v188, v188, v189
	v_cvt_pk_bf16_f32 v189, v190, v191
	v_cvt_pk_bf16_f32 v192, v192, v193
	v_cvt_pk_bf16_f32 v193, v194, v195
	v_cvt_pk_bf16_f32 v196, v196, v197
	v_cvt_pk_bf16_f32 v197, v198, v199
	v_cvt_pk_bf16_f32 v200, v200, v201
	v_cvt_pk_bf16_f32 v201, v202, v203
	v_cvt_pk_bf16_f32 v208, v208, v209
	v_cvt_pk_bf16_f32 v209, v210, v211
	v_cvt_pk_bf16_f32 v212, v212, v213
	v_cvt_pk_bf16_f32 v213, v214, v215
	v_cvt_pk_bf16_f32 v216, v216, v217
	v_cvt_pk_bf16_f32 v217, v218, v219
	v_cvt_pk_bf16_f32 v220, v220, v221
	v_cvt_pk_bf16_f32 v221, v222, v223
	v_cvt_pk_bf16_f32 v224, v224, v225
	v_cvt_pk_bf16_f32 v225, v226, v227
	v_cvt_pk_bf16_f32 v228, v228, v229
	v_cvt_pk_bf16_f32 v229, v230, v231
	v_cvt_pk_bf16_f32 v232, v232, v233
	v_cvt_pk_bf16_f32 v233, v234, v235
	v_cvt_pk_bf16_f32 v236, v236, v237
	v_cvt_pk_bf16_f32 v237, v238, v239
	v_cvt_pk_bf16_f32 v240, v240, v241
	v_cvt_pk_bf16_f32 v241, v242, v243
	v_cvt_pk_bf16_f32 v244, v244, v245
	v_cvt_pk_bf16_f32 v245, v246, v247
	v_cvt_pk_bf16_f32 v248, v248, v249
	v_cvt_pk_bf16_f32 v249, v250, v251
	global_store_dwordx2 v[2:3], v[184:185], off offset:-1024
	global_store_dwordx2 v[2:3], v[188:189], off offset:-896
	global_store_dwordx2 v[2:3], v[192:193], off offset:-768
	global_store_dwordx2 v[2:3], v[196:197], off offset:-640
	global_store_dwordx2 v[2:3], v[200:201], off offset:-512
	global_store_dwordx2 v[2:3], v[208:209], off offset:-384
	global_store_dwordx2 v[2:3], v[212:213], off offset:-256
	global_store_dwordx2 v[2:3], v[216:217], off offset:-128
	global_store_dwordx2 v[2:3], v[220:221], off
	global_store_dwordx2 v[2:3], v[224:225], off offset:128
	global_store_dwordx2 v[2:3], v[228:229], off offset:256
	global_store_dwordx2 v[2:3], v[232:233], off offset:384
	global_store_dwordx2 v[2:3], v[236:237], off offset:512
	global_store_dwordx2 v[2:3], v[240:241], off offset:640
	global_store_dwordx2 v[2:3], v[244:245], off offset:768
	global_store_dwordx2 v[2:3], v[248:249], off offset:896
	s_mov_b64 s[16:17], 0x800
	v_lshl_add_u64 v[2:3], v[2:3], 0, s[16:17]
	v_add_co_u32_e32 v10, vcc, 0x8000, v10
	s_nop 1
	v_addc_co_u32_e32 v11, vcc, 0, v11, vcc
	global_load_dwordx4 v[184:187], v[10:11], off
	global_load_dwordx4 v[188:191], v[10:11], off offset:2048
	v_add_co_u32_e32 v12, vcc, 0x1000, v10
	s_nop 1
	v_addc_co_u32_e32 v13, vcc, 0, v11, vcc
	global_load_dwordx4 v[192:195], v[12:13], off
	global_load_dwordx4 v[196:199], v[12:13], off offset:2048
	v_add_co_u32_e32 v12, vcc, 0x2000, v10
	s_nop 1
	v_addc_co_u32_e32 v13, vcc, 0, v11, vcc
	global_load_dwordx4 v[200:203], v[12:13], off
	global_load_dwordx4 v[208:211], v[12:13], off offset:2048
	v_add_co_u32_e32 v12, vcc, 0x3000, v10
	s_nop 1
	v_addc_co_u32_e32 v13, vcc, 0, v11, vcc
	global_load_dwordx4 v[212:215], v[12:13], off
	global_load_dwordx4 v[216:219], v[12:13], off offset:2048
	v_add_co_u32_e32 v12, vcc, 0x4000, v10
	s_nop 1
	v_addc_co_u32_e32 v13, vcc, 0, v11, vcc
	global_load_dwordx4 v[220:223], v[12:13], off
	global_load_dwordx4 v[224:227], v[12:13], off offset:2048
	v_add_co_u32_e32 v12, vcc, 0x5000, v10
	s_nop 1
	v_addc_co_u32_e32 v13, vcc, 0, v11, vcc
	global_load_dwordx4 v[228:231], v[12:13], off
	global_load_dwordx4 v[232:235], v[12:13], off offset:2048
	v_add_co_u32_e32 v12, vcc, 0x6000, v10
	s_nop 1
	v_addc_co_u32_e32 v13, vcc, 0, v11, vcc
	global_load_dwordx4 v[236:239], v[12:13], off
	global_load_dwordx4 v[240:243], v[12:13], off offset:2048
	v_add_co_u32_e32 v12, vcc, 0x7000, v10
	s_nop 1
	v_addc_co_u32_e32 v13, vcc, 0, v11, vcc
	global_load_dwordx4 v[244:247], v[12:13], off
	global_load_dwordx4 v[248:251], v[12:13], off offset:2048
	s_waitcnt vmcnt(32)
	v_cvt_pk_bf16_f32 v120, v120, v121
	v_cvt_pk_bf16_f32 v121, v122, v123
	v_cvt_pk_bf16_f32 v124, v124, v125
	v_cvt_pk_bf16_f32 v125, v126, v127
	v_cvt_pk_bf16_f32 v128, v128, v129
	v_cvt_pk_bf16_f32 v129, v130, v131
	v_cvt_pk_bf16_f32 v132, v132, v133
	v_cvt_pk_bf16_f32 v133, v134, v135
	v_cvt_pk_bf16_f32 v136, v136, v137
	v_cvt_pk_bf16_f32 v137, v138, v139
	v_cvt_pk_bf16_f32 v140, v140, v141
	v_cvt_pk_bf16_f32 v141, v142, v143
	v_cvt_pk_bf16_f32 v144, v144, v145
	v_cvt_pk_bf16_f32 v145, v146, v147
	v_cvt_pk_bf16_f32 v148, v148, v149
	v_cvt_pk_bf16_f32 v149, v150, v151
	v_cvt_pk_bf16_f32 v152, v152, v153
	v_cvt_pk_bf16_f32 v153, v154, v155
	v_cvt_pk_bf16_f32 v156, v156, v157
	v_cvt_pk_bf16_f32 v157, v158, v159
	v_cvt_pk_bf16_f32 v160, v160, v161
	v_cvt_pk_bf16_f32 v161, v162, v163
	v_cvt_pk_bf16_f32 v164, v164, v165
	v_cvt_pk_bf16_f32 v165, v166, v167
	v_cvt_pk_bf16_f32 v168, v168, v169
	v_cvt_pk_bf16_f32 v169, v170, v171
	v_cvt_pk_bf16_f32 v172, v172, v173
	v_cvt_pk_bf16_f32 v173, v174, v175
	v_cvt_pk_bf16_f32 v176, v176, v177
	v_cvt_pk_bf16_f32 v177, v178, v179
	v_cvt_pk_bf16_f32 v180, v180, v181
	v_cvt_pk_bf16_f32 v181, v182, v183
	global_store_dwordx2 v[2:3], v[120:121], off offset:-1024
	global_store_dwordx2 v[2:3], v[124:125], off offset:-896
	global_store_dwordx2 v[2:3], v[128:129], off offset:-768
	global_store_dwordx2 v[2:3], v[132:133], off offset:-640
	global_store_dwordx2 v[2:3], v[136:137], off offset:-512
	global_store_dwordx2 v[2:3], v[140:141], off offset:-384
	global_store_dwordx2 v[2:3], v[144:145], off offset:-256
	global_store_dwordx2 v[2:3], v[148:149], off offset:-128
	global_store_dwordx2 v[2:3], v[152:153], off
	global_store_dwordx2 v[2:3], v[156:157], off offset:128
	global_store_dwordx2 v[2:3], v[160:161], off offset:256
	global_store_dwordx2 v[2:3], v[164:165], off offset:384
	global_store_dwordx2 v[2:3], v[168:169], off offset:512
	global_store_dwordx2 v[2:3], v[172:173], off offset:640
	global_store_dwordx2 v[2:3], v[176:177], off offset:768
	global_store_dwordx2 v[2:3], v[180:181], off offset:896
	s_mov_b64 s[16:17], 0x800
	v_lshl_add_u64 v[2:3], v[2:3], 0, s[16:17]
	s_waitcnt vmcnt(16)
	v_cvt_pk_bf16_f32 v184, v184, v185
	v_cvt_pk_bf16_f32 v185, v186, v187
	v_cvt_pk_bf16_f32 v188, v188, v189
	v_cvt_pk_bf16_f32 v189, v190, v191
	v_cvt_pk_bf16_f32 v192, v192, v193
	v_cvt_pk_bf16_f32 v193, v194, v195
	v_cvt_pk_bf16_f32 v196, v196, v197
	v_cvt_pk_bf16_f32 v197, v198, v199
	v_cvt_pk_bf16_f32 v200, v200, v201
	v_cvt_pk_bf16_f32 v201, v202, v203
	v_cvt_pk_bf16_f32 v208, v208, v209
	v_cvt_pk_bf16_f32 v209, v210, v211
	v_cvt_pk_bf16_f32 v212, v212, v213
	v_cvt_pk_bf16_f32 v213, v214, v215
	v_cvt_pk_bf16_f32 v216, v216, v217
	v_cvt_pk_bf16_f32 v217, v218, v219
	v_cvt_pk_bf16_f32 v220, v220, v221
	v_cvt_pk_bf16_f32 v221, v222, v223
	v_cvt_pk_bf16_f32 v224, v224, v225
	v_cvt_pk_bf16_f32 v225, v226, v227
	v_cvt_pk_bf16_f32 v228, v228, v229
	v_cvt_pk_bf16_f32 v229, v230, v231
	v_cvt_pk_bf16_f32 v232, v232, v233
	v_cvt_pk_bf16_f32 v233, v234, v235
	v_cvt_pk_bf16_f32 v236, v236, v237
	v_cvt_pk_bf16_f32 v237, v238, v239
	v_cvt_pk_bf16_f32 v240, v240, v241
	v_cvt_pk_bf16_f32 v241, v242, v243
	v_cvt_pk_bf16_f32 v244, v244, v245
	v_cvt_pk_bf16_f32 v245, v246, v247
	v_cvt_pk_bf16_f32 v248, v248, v249
	v_cvt_pk_bf16_f32 v249, v250, v251
	global_store_dwordx2 v[2:3], v[184:185], off offset:-1024
	global_store_dwordx2 v[2:3], v[188:189], off offset:-896
	global_store_dwordx2 v[2:3], v[192:193], off offset:-768
	global_store_dwordx2 v[2:3], v[196:197], off offset:-640
	global_store_dwordx2 v[2:3], v[200:201], off offset:-512
	global_store_dwordx2 v[2:3], v[208:209], off offset:-384
	global_store_dwordx2 v[2:3], v[212:213], off offset:-256
	global_store_dwordx2 v[2:3], v[216:217], off offset:-128
	global_store_dwordx2 v[2:3], v[220:221], off
	global_store_dwordx2 v[2:3], v[224:225], off offset:128
	global_store_dwordx2 v[2:3], v[228:229], off offset:256
	global_store_dwordx2 v[2:3], v[232:233], off offset:384
	global_store_dwordx2 v[2:3], v[236:237], off offset:512
	global_store_dwordx2 v[2:3], v[240:241], off offset:640
	global_store_dwordx2 v[2:3], v[244:245], off offset:768
	global_store_dwordx2 v[2:3], v[248:249], off offset:896
	s_mov_b64 s[16:17], 0x800
	v_lshl_add_u64 v[2:3], v[2:3], 0, s[16:17]
	s_mov_b64 s[4:5], 0x40000
